# GEMM2 hook math with packed f32 multiplies (same per-element operations, 16% fewer VALU instructions)
# speedup vs baseline: 1.0243x; 1.0030x over previous
.LBB0_867:
	s_and_b32 s2, s97, 22
	s_cmp_lg_u32 s2, 16
	s_cselect_b64 s[2:3], -1, 0
	s_xor_b64 s[4:5], s[42:43], -1
	s_or_b64 s[2:3], s[4:5], s[2:3]
	s_and_b64 vcc, exec, s[2:3]
	s_cbranch_vccnz .LBB0_869
	s_cmp_eq_u32 s97, 16
	v_mov_b32_e32 v1, v0
	s_cselect_b32 s34, 0, 0x1000
	s_addk_i32 s34, 0x800
	v_add_u32_e32 v1, v1, v212
	v_lshl_add_u64 v[2:3], v[216:217], 0, s[34:35]
	s_mov_b32 s34, 0xbfb8aa3b
	v_mad_i64_i32 v[218:219], s[2:3], v1, s20, v[2:3]
	global_load_dwordx4 v[132:135], v[218:219], off offset:-2048
	global_load_dwordx4 v[136:139], v[218:219], off offset:2048
	global_load_dwordx4 v[140:143], v[218:219], off offset:-1792
	global_load_dwordx4 v[144:147], v[218:219], off offset:2304
	v_add_u32_e32 v213, 16, v1
	v_mad_i64_i32 v[218:219], s[2:3], v213, s20, v[2:3]
	global_load_dwordx4 v[148:151], v[218:219], off offset:-2048
	global_load_dwordx4 v[152:155], v[218:219], off offset:2048
	global_load_dwordx4 v[156:159], v[218:219], off offset:-1792
	global_load_dwordx4 v[160:163], v[218:219], off offset:2304
	v_add_u32_e32 v213, 32, v1
	v_mad_i64_i32 v[218:219], s[2:3], v213, s20, v[2:3]
	global_load_dwordx4 v[164:167], v[218:219], off offset:-2048
	global_load_dwordx4 v[168:171], v[218:219], off offset:2048
	global_load_dwordx4 v[172:175], v[218:219], off offset:-1792
	global_load_dwordx4 v[176:179], v[218:219], off offset:2304
	v_add_u32_e32 v213, 48, v1
	v_mad_i64_i32 v[218:219], s[2:3], v213, s20, v[2:3]
	global_load_dwordx4 v[180:183], v[218:219], off offset:-2048
	global_load_dwordx4 v[184:187], v[218:219], off offset:2048
	global_load_dwordx4 v[188:191], v[218:219], off offset:-1792
	global_load_dwordx4 v[192:195], v[218:219], off offset:2304
	s_waitcnt vmcnt(14)
	v_lshlrev_b32_e32 v244, 16, v132
	v_and_b32_e32 v245, 0xffff0000, v132
	v_lshlrev_b32_e32 v246, 16, v133
	v_and_b32_e32 v247, 0xffff0000, v133
	v_lshlrev_b32_e32 v132, 16, v134
	v_and_b32_e32 v133, 0xffff0000, v134
	v_lshlrev_b32_e32 v134, 16, v135
	v_and_b32_e32 v135, 0xffff0000, v135
	v_lshlrev_b32_e32 v248, 16, v136
	v_and_b32_e32 v249, 0xffff0000, v136
	v_lshlrev_b32_e32 v250, 16, v137
	v_and_b32_e32 v251, 0xffff0000, v137
	v_lshlrev_b32_e32 v136, 16, v138
	v_and_b32_e32 v137, 0xffff0000, v138
	v_lshlrev_b32_e32 v138, 16, v139
	v_and_b32_e32 v139, 0xffff0000, v139
	v_pk_mul_f32 v[244:245], v[244:245], s[34:35] op_sel_hi:[1,0]
	v_pk_mul_f32 v[246:247], v[246:247], s[34:35] op_sel_hi:[1,0]
	v_pk_mul_f32 v[132:133], v[132:133], s[34:35] op_sel_hi:[1,0]
	v_pk_mul_f32 v[134:135], v[134:135], s[34:35] op_sel_hi:[1,0]
	v_pk_mul_f32 v[248:249], v[248:249], s[34:35] op_sel_hi:[1,0]
	v_pk_mul_f32 v[250:251], v[250:251], s[34:35] op_sel_hi:[1,0]
	v_pk_mul_f32 v[136:137], v[136:137], s[34:35] op_sel_hi:[1,0]
	v_pk_mul_f32 v[138:139], v[138:139], s[34:35] op_sel_hi:[1,0]
	v_exp_f32_e32 v244, v244
	v_exp_f32_e32 v245, v245
	v_exp_f32_e32 v246, v246
	v_exp_f32_e32 v247, v247
	v_exp_f32_e32 v132, v132
	v_exp_f32_e32 v133, v133
	v_exp_f32_e32 v134, v134
	v_exp_f32_e32 v135, v135
	v_exp_f32_e32 v248, v248
	v_exp_f32_e32 v249, v249
	v_exp_f32_e32 v250, v250
	v_exp_f32_e32 v251, v251
	v_exp_f32_e32 v136, v136
	v_exp_f32_e32 v137, v137
	v_exp_f32_e32 v138, v138
	v_exp_f32_e32 v139, v139
	v_pk_add_f32 v[244:245], v[244:245], 1.0 op_sel_hi:[1,0]
	v_pk_add_f32 v[246:247], v[246:247], 1.0 op_sel_hi:[1,0]
	v_pk_add_f32 v[132:133], v[132:133], 1.0 op_sel_hi:[1,0]
	v_pk_add_f32 v[134:135], v[134:135], 1.0 op_sel_hi:[1,0]
	v_pk_add_f32 v[248:249], v[248:249], 1.0 op_sel_hi:[1,0]
	v_pk_add_f32 v[250:251], v[250:251], 1.0 op_sel_hi:[1,0]
	v_pk_add_f32 v[136:137], v[136:137], 1.0 op_sel_hi:[1,0]
	v_pk_add_f32 v[138:139], v[138:139], 1.0 op_sel_hi:[1,0]
	v_rcp_f32_e32 v244, v244
	v_rcp_f32_e32 v245, v245
	v_rcp_f32_e32 v246, v246
	v_rcp_f32_e32 v247, v247
	v_rcp_f32_e32 v132, v132
	v_rcp_f32_e32 v133, v133
	v_rcp_f32_e32 v134, v134
	v_rcp_f32_e32 v135, v135
	v_pk_mul_f32 v[248:249], v[248:249], v[244:245]
	v_pk_mul_f32 v[250:251], v[250:251], v[246:247]
	v_pk_mul_f32 v[136:137], v[136:137], v[132:133]
	v_pk_mul_f32 v[138:139], v[138:139], v[134:135]
	v_pk_mul_f32 v[128:129], v[128:129], v[248:249]
	v_pk_mul_f32 v[130:131], v[130:131], v[250:251]
	v_pk_mul_f32 v[124:125], v[124:125], v[136:137]
	v_pk_mul_f32 v[126:127], v[126:127], v[138:139]
	v_add_u32_e32 v213, 128, v1
	v_mad_i64_i32 v[218:219], s[2:3], v213, s20, v[2:3]
	global_load_dwordx4 v[132:135], v[218:219], off offset:-2048
	global_load_dwordx4 v[136:139], v[218:219], off offset:2048
	s_waitcnt vmcnt(14)
	v_lshlrev_b32_e32 v244, 16, v140
	v_and_b32_e32 v245, 0xffff0000, v140
	v_lshlrev_b32_e32 v246, 16, v141
	v_and_b32_e32 v247, 0xffff0000, v141
	v_lshlrev_b32_e32 v140, 16, v142
	v_and_b32_e32 v141, 0xffff0000, v142
	v_lshlrev_b32_e32 v142, 16, v143
	v_and_b32_e32 v143, 0xffff0000, v143
	v_lshlrev_b32_e32 v248, 16, v144
	v_and_b32_e32 v249, 0xffff0000, v144
	v_lshlrev_b32_e32 v250, 16, v145
	v_and_b32_e32 v251, 0xffff0000, v145
	v_lshlrev_b32_e32 v144, 16, v146
	v_and_b32_e32 v145, 0xffff0000, v146
	v_lshlrev_b32_e32 v146, 16, v147
	v_and_b32_e32 v147, 0xffff0000, v147
	v_pk_mul_f32 v[244:245], v[244:245], s[34:35] op_sel_hi:[1,0]
	v_pk_mul_f32 v[246:247], v[246:247], s[34:35] op_sel_hi:[1,0]
	v_pk_mul_f32 v[140:141], v[140:141], s[34:35] op_sel_hi:[1,0]
	v_pk_mul_f32 v[142:143], v[142:143], s[34:35] op_sel_hi:[1,0]
	v_pk_mul_f32 v[248:249], v[248:249], s[34:35] op_sel_hi:[1,0]
	v_pk_mul_f32 v[250:251], v[250:251], s[34:35] op_sel_hi:[1,0]
	v_pk_mul_f32 v[144:145], v[144:145], s[34:35] op_sel_hi:[1,0]
	v_pk_mul_f32 v[146:147], v[146:147], s[34:35] op_sel_hi:[1,0]
	v_exp_f32_e32 v244, v244
	v_exp_f32_e32 v245, v245
	v_exp_f32_e32 v246, v246
	v_exp_f32_e32 v247, v247
	v_exp_f32_e32 v140, v140
	v_exp_f32_e32 v141, v141
	v_exp_f32_e32 v142, v142
	v_exp_f32_e32 v143, v143
	v_exp_f32_e32 v248, v248
	v_exp_f32_e32 v249, v249
	v_exp_f32_e32 v250, v250
	v_exp_f32_e32 v251, v251
	v_exp_f32_e32 v144, v144
	v_exp_f32_e32 v145, v145
	v_exp_f32_e32 v146, v146
	v_exp_f32_e32 v147, v147
	v_pk_add_f32 v[244:245], v[244:245], 1.0 op_sel_hi:[1,0]
	v_pk_add_f32 v[246:247], v[246:247], 1.0 op_sel_hi:[1,0]
	v_pk_add_f32 v[140:141], v[140:141], 1.0 op_sel_hi:[1,0]
	v_pk_add_f32 v[142:143], v[142:143], 1.0 op_sel_hi:[1,0]
	v_pk_add_f32 v[248:249], v[248:249], 1.0 op_sel_hi:[1,0]
	v_pk_add_f32 v[250:251], v[250:251], 1.0 op_sel_hi:[1,0]
	v_pk_add_f32 v[144:145], v[144:145], 1.0 op_sel_hi:[1,0]
	v_pk_add_f32 v[146:147], v[146:147], 1.0 op_sel_hi:[1,0]
	v_rcp_f32_e32 v244, v244
	v_rcp_f32_e32 v245, v245
	v_rcp_f32_e32 v246, v246
	v_rcp_f32_e32 v247, v247
	v_rcp_f32_e32 v140, v140
	v_rcp_f32_e32 v141, v141
	v_rcp_f32_e32 v142, v142
	v_rcp_f32_e32 v143, v143
	v_pk_mul_f32 v[248:249], v[248:249], v[244:245]
	v_pk_mul_f32 v[250:251], v[250:251], v[246:247]
	v_pk_mul_f32 v[144:145], v[144:145], v[140:141]
	v_pk_mul_f32 v[146:147], v[146:147], v[142:143]
	v_pk_mul_f32 v[120:121], v[120:121], v[248:249]
	v_pk_mul_f32 v[122:123], v[122:123], v[250:251]
	v_pk_mul_f32 v[116:117], v[116:117], v[144:145]
	v_pk_mul_f32 v[118:119], v[118:119], v[146:147]
	global_load_dwordx4 v[140:143], v[218:219], off offset:-1792
	global_load_dwordx4 v[144:147], v[218:219], off offset:2304
	s_waitcnt vmcnt(14)
	v_lshlrev_b32_e32 v244, 16, v148
	v_and_b32_e32 v245, 0xffff0000, v148
	v_lshlrev_b32_e32 v246, 16, v149
	v_and_b32_e32 v247, 0xffff0000, v149
	v_lshlrev_b32_e32 v148, 16, v150
	v_and_b32_e32 v149, 0xffff0000, v150
	v_lshlrev_b32_e32 v150, 16, v151
	v_and_b32_e32 v151, 0xffff0000, v151
	v_lshlrev_b32_e32 v248, 16, v152
	v_and_b32_e32 v249, 0xffff0000, v152
	v_lshlrev_b32_e32 v250, 16, v153
	v_and_b32_e32 v251, 0xffff0000, v153
	v_lshlrev_b32_e32 v152, 16, v154
	v_and_b32_e32 v153, 0xffff0000, v154
	v_lshlrev_b32_e32 v154, 16, v155
	v_and_b32_e32 v155, 0xffff0000, v155
	v_pk_mul_f32 v[244:245], v[244:245], s[34:35] op_sel_hi:[1,0]
	v_pk_mul_f32 v[246:247], v[246:247], s[34:35] op_sel_hi:[1,0]
	v_pk_mul_f32 v[148:149], v[148:149], s[34:35] op_sel_hi:[1,0]
	v_pk_mul_f32 v[150:151], v[150:151], s[34:35] op_sel_hi:[1,0]
	v_pk_mul_f32 v[248:249], v[248:249], s[34:35] op_sel_hi:[1,0]
	v_pk_mul_f32 v[250:251], v[250:251], s[34:35] op_sel_hi:[1,0]
	v_pk_mul_f32 v[152:153], v[152:153], s[34:35] op_sel_hi:[1,0]
	v_pk_mul_f32 v[154:155], v[154:155], s[34:35] op_sel_hi:[1,0]
	v_exp_f32_e32 v244, v244
	v_exp_f32_e32 v245, v245
	v_exp_f32_e32 v246, v246
	v_exp_f32_e32 v247, v247
	v_exp_f32_e32 v148, v148
	v_exp_f32_e32 v149, v149
	v_exp_f32_e32 v150, v150
	v_exp_f32_e32 v151, v151
	v_exp_f32_e32 v248, v248
	v_exp_f32_e32 v249, v249
	v_exp_f32_e32 v250, v250
	v_exp_f32_e32 v251, v251
	v_exp_f32_e32 v152, v152
	v_exp_f32_e32 v153, v153
	v_exp_f32_e32 v154, v154
	v_exp_f32_e32 v155, v155
	v_pk_add_f32 v[244:245], v[244:245], 1.0 op_sel_hi:[1,0]
	v_pk_add_f32 v[246:247], v[246:247], 1.0 op_sel_hi:[1,0]
	v_pk_add_f32 v[148:149], v[148:149], 1.0 op_sel_hi:[1,0]
	v_pk_add_f32 v[150:151], v[150:151], 1.0 op_sel_hi:[1,0]
	v_pk_add_f32 v[248:249], v[248:249], 1.0 op_sel_hi:[1,0]
	v_pk_add_f32 v[250:251], v[250:251], 1.0 op_sel_hi:[1,0]
	v_pk_add_f32 v[152:153], v[152:153], 1.0 op_sel_hi:[1,0]
	v_pk_add_f32 v[154:155], v[154:155], 1.0 op_sel_hi:[1,0]
	v_rcp_f32_e32 v244, v244
	v_rcp_f32_e32 v245, v245
	v_rcp_f32_e32 v246, v246
	v_rcp_f32_e32 v247, v247
	v_rcp_f32_e32 v148, v148
	v_rcp_f32_e32 v149, v149
	v_rcp_f32_e32 v150, v150
	v_rcp_f32_e32 v151, v151
	v_pk_mul_f32 v[248:249], v[248:249], v[244:245]
	v_pk_mul_f32 v[250:251], v[250:251], v[246:247]
	v_pk_mul_f32 v[152:153], v[152:153], v[148:149]
	v_pk_mul_f32 v[154:155], v[154:155], v[150:151]
	v_pk_mul_f32 v[112:113], v[112:113], v[248:249]
	v_pk_mul_f32 v[114:115], v[114:115], v[250:251]
	v_pk_mul_f32 v[108:109], v[108:109], v[152:153]
	v_pk_mul_f32 v[110:111], v[110:111], v[154:155]
	v_add_u32_e32 v213, 144, v1
	v_mad_i64_i32 v[218:219], s[2:3], v213, s20, v[2:3]
	global_load_dwordx4 v[148:151], v[218:219], off offset:-2048
	global_load_dwordx4 v[152:155], v[218:219], off offset:2048
	s_waitcnt vmcnt(14)
	v_lshlrev_b32_e32 v244, 16, v156
	v_and_b32_e32 v245, 0xffff0000, v156
	v_lshlrev_b32_e32 v246, 16, v157
	v_and_b32_e32 v247, 0xffff0000, v157
	v_lshlrev_b32_e32 v156, 16, v158
	v_and_b32_e32 v157, 0xffff0000, v158
	v_lshlrev_b32_e32 v158, 16, v159
	v_and_b32_e32 v159, 0xffff0000, v159
	v_lshlrev_b32_e32 v248, 16, v160
	v_and_b32_e32 v249, 0xffff0000, v160
	v_lshlrev_b32_e32 v250, 16, v161
	v_and_b32_e32 v251, 0xffff0000, v161
	v_lshlrev_b32_e32 v160, 16, v162
	v_and_b32_e32 v161, 0xffff0000, v162
	v_lshlrev_b32_e32 v162, 16, v163
	v_and_b32_e32 v163, 0xffff0000, v163
	v_pk_mul_f32 v[244:245], v[244:245], s[34:35] op_sel_hi:[1,0]
	v_pk_mul_f32 v[246:247], v[246:247], s[34:35] op_sel_hi:[1,0]
	v_pk_mul_f32 v[156:157], v[156:157], s[34:35] op_sel_hi:[1,0]
	v_pk_mul_f32 v[158:159], v[158:159], s[34:35] op_sel_hi:[1,0]
	v_pk_mul_f32 v[248:249], v[248:249], s[34:35] op_sel_hi:[1,0]
	v_pk_mul_f32 v[250:251], v[250:251], s[34:35] op_sel_hi:[1,0]
	v_pk_mul_f32 v[160:161], v[160:161], s[34:35] op_sel_hi:[1,0]
	v_pk_mul_f32 v[162:163], v[162:163], s[34:35] op_sel_hi:[1,0]
	v_exp_f32_e32 v244, v244
	v_exp_f32_e32 v245, v245
	v_exp_f32_e32 v246, v246
	v_exp_f32_e32 v247, v247
	v_exp_f32_e32 v156, v156
	v_exp_f32_e32 v157, v157
	v_exp_f32_e32 v158, v158
	v_exp_f32_e32 v159, v159
	v_exp_f32_e32 v248, v248
	v_exp_f32_e32 v249, v249
	v_exp_f32_e32 v250, v250
	v_exp_f32_e32 v251, v251
	v_exp_f32_e32 v160, v160
	v_exp_f32_e32 v161, v161
	v_exp_f32_e32 v162, v162
	v_exp_f32_e32 v163, v163
	v_pk_add_f32 v[244:245], v[244:245], 1.0 op_sel_hi:[1,0]
	v_pk_add_f32 v[246:247], v[246:247], 1.0 op_sel_hi:[1,0]
	v_pk_add_f32 v[156:157], v[156:157], 1.0 op_sel_hi:[1,0]
	v_pk_add_f32 v[158:159], v[158:159], 1.0 op_sel_hi:[1,0]
	v_pk_add_f32 v[248:249], v[248:249], 1.0 op_sel_hi:[1,0]
	v_pk_add_f32 v[250:251], v[250:251], 1.0 op_sel_hi:[1,0]
	v_pk_add_f32 v[160:161], v[160:161], 1.0 op_sel_hi:[1,0]
	v_pk_add_f32 v[162:163], v[162:163], 1.0 op_sel_hi:[1,0]
	v_rcp_f32_e32 v244, v244
	v_rcp_f32_e32 v245, v245
	v_rcp_f32_e32 v246, v246
	v_rcp_f32_e32 v247, v247
	v_rcp_f32_e32 v156, v156
	v_rcp_f32_e32 v157, v157
	v_rcp_f32_e32 v158, v158
	v_rcp_f32_e32 v159, v159
	v_pk_mul_f32 v[248:249], v[248:249], v[244:245]
	v_pk_mul_f32 v[250:251], v[250:251], v[246:247]
	v_pk_mul_f32 v[160:161], v[160:161], v[156:157]
	v_pk_mul_f32 v[162:163], v[162:163], v[158:159]
	v_pk_mul_f32 v[104:105], v[104:105], v[248:249]
	v_pk_mul_f32 v[106:107], v[106:107], v[250:251]
	v_pk_mul_f32 v[100:101], v[100:101], v[160:161]
	v_pk_mul_f32 v[102:103], v[102:103], v[162:163]
	global_load_dwordx4 v[156:159], v[218:219], off offset:-1792
	global_load_dwordx4 v[160:163], v[218:219], off offset:2304
	s_waitcnt vmcnt(14)
	v_lshlrev_b32_e32 v244, 16, v164
	v_and_b32_e32 v245, 0xffff0000, v164
	v_lshlrev_b32_e32 v246, 16, v165
	v_and_b32_e32 v247, 0xffff0000, v165
	v_lshlrev_b32_e32 v164, 16, v166
	v_and_b32_e32 v165, 0xffff0000, v166
	v_lshlrev_b32_e32 v166, 16, v167
	v_and_b32_e32 v167, 0xffff0000, v167
	v_lshlrev_b32_e32 v248, 16, v168
	v_and_b32_e32 v249, 0xffff0000, v168
	v_lshlrev_b32_e32 v250, 16, v169
	v_and_b32_e32 v251, 0xffff0000, v169
	v_lshlrev_b32_e32 v168, 16, v170
	v_and_b32_e32 v169, 0xffff0000, v170
	v_lshlrev_b32_e32 v170, 16, v171
	v_and_b32_e32 v171, 0xffff0000, v171
	v_pk_mul_f32 v[244:245], v[244:245], s[34:35] op_sel_hi:[1,0]
	v_pk_mul_f32 v[246:247], v[246:247], s[34:35] op_sel_hi:[1,0]
	v_pk_mul_f32 v[164:165], v[164:165], s[34:35] op_sel_hi:[1,0]
	v_pk_mul_f32 v[166:167], v[166:167], s[34:35] op_sel_hi:[1,0]
	v_pk_mul_f32 v[248:249], v[248:249], s[34:35] op_sel_hi:[1,0]
	v_pk_mul_f32 v[250:251], v[250:251], s[34:35] op_sel_hi:[1,0]
	v_pk_mul_f32 v[168:169], v[168:169], s[34:35] op_sel_hi:[1,0]
	v_pk_mul_f32 v[170:171], v[170:171], s[34:35] op_sel_hi:[1,0]
	v_exp_f32_e32 v244, v244
	v_exp_f32_e32 v245, v245
	v_exp_f32_e32 v246, v246
	v_exp_f32_e32 v247, v247
	v_exp_f32_e32 v164, v164
	v_exp_f32_e32 v165, v165
	v_exp_f32_e32 v166, v166
	v_exp_f32_e32 v167, v167
	v_exp_f32_e32 v248, v248
	v_exp_f32_e32 v249, v249
	v_exp_f32_e32 v250, v250
	v_exp_f32_e32 v251, v251
	v_exp_f32_e32 v168, v168
	v_exp_f32_e32 v169, v169
	v_exp_f32_e32 v170, v170
	v_exp_f32_e32 v171, v171
	v_pk_add_f32 v[244:245], v[244:245], 1.0 op_sel_hi:[1,0]
	v_pk_add_f32 v[246:247], v[246:247], 1.0 op_sel_hi:[1,0]
	v_pk_add_f32 v[164:165], v[164:165], 1.0 op_sel_hi:[1,0]
	v_pk_add_f32 v[166:167], v[166:167], 1.0 op_sel_hi:[1,0]
	v_pk_add_f32 v[248:249], v[248:249], 1.0 op_sel_hi:[1,0]
	v_pk_add_f32 v[250:251], v[250:251], 1.0 op_sel_hi:[1,0]
	v_pk_add_f32 v[168:169], v[168:169], 1.0 op_sel_hi:[1,0]
	v_pk_add_f32 v[170:171], v[170:171], 1.0 op_sel_hi:[1,0]
	v_rcp_f32_e32 v244, v244
	v_rcp_f32_e32 v245, v245
	v_rcp_f32_e32 v246, v246
	v_rcp_f32_e32 v247, v247
	v_rcp_f32_e32 v164, v164
	v_rcp_f32_e32 v165, v165
	v_rcp_f32_e32 v166, v166
	v_rcp_f32_e32 v167, v167
	v_pk_mul_f32 v[248:249], v[248:249], v[244:245]
	v_pk_mul_f32 v[250:251], v[250:251], v[246:247]
	v_pk_mul_f32 v[168:169], v[168:169], v[164:165]
	v_pk_mul_f32 v[170:171], v[170:171], v[166:167]
	v_pk_mul_f32 v[96:97], v[96:97], v[248:249]
	v_pk_mul_f32 v[98:99], v[98:99], v[250:251]
	v_pk_mul_f32 v[92:93], v[92:93], v[168:169]
	v_pk_mul_f32 v[94:95], v[94:95], v[170:171]
	v_add_u32_e32 v213, 160, v1
	v_mad_i64_i32 v[218:219], s[2:3], v213, s20, v[2:3]
	global_load_dwordx4 v[164:167], v[218:219], off offset:-2048
	global_load_dwordx4 v[168:171], v[218:219], off offset:2048
	s_waitcnt vmcnt(14)
	v_lshlrev_b32_e32 v244, 16, v172
	v_and_b32_e32 v245, 0xffff0000, v172
	v_lshlrev_b32_e32 v246, 16, v173
	v_and_b32_e32 v247, 0xffff0000, v173
	v_lshlrev_b32_e32 v172, 16, v174
	v_and_b32_e32 v173, 0xffff0000, v174
	v_lshlrev_b32_e32 v174, 16, v175
	v_and_b32_e32 v175, 0xffff0000, v175
	v_lshlrev_b32_e32 v248, 16, v176
	v_and_b32_e32 v249, 0xffff0000, v176
	v_lshlrev_b32_e32 v250, 16, v177
	v_and_b32_e32 v251, 0xffff0000, v177
	v_lshlrev_b32_e32 v176, 16, v178
	v_and_b32_e32 v177, 0xffff0000, v178
	v_lshlrev_b32_e32 v178, 16, v179
	v_and_b32_e32 v179, 0xffff0000, v179
	v_pk_mul_f32 v[244:245], v[244:245], s[34:35] op_sel_hi:[1,0]
	v_pk_mul_f32 v[246:247], v[246:247], s[34:35] op_sel_hi:[1,0]
	v_pk_mul_f32 v[172:173], v[172:173], s[34:35] op_sel_hi:[1,0]
	v_pk_mul_f32 v[174:175], v[174:175], s[34:35] op_sel_hi:[1,0]
	v_pk_mul_f32 v[248:249], v[248:249], s[34:35] op_sel_hi:[1,0]
	v_pk_mul_f32 v[250:251], v[250:251], s[34:35] op_sel_hi:[1,0]
	v_pk_mul_f32 v[176:177], v[176:177], s[34:35] op_sel_hi:[1,0]
	v_pk_mul_f32 v[178:179], v[178:179], s[34:35] op_sel_hi:[1,0]
	v_exp_f32_e32 v244, v244
	v_exp_f32_e32 v245, v245
	v_exp_f32_e32 v246, v246
	v_exp_f32_e32 v247, v247
	v_exp_f32_e32 v172, v172
	v_exp_f32_e32 v173, v173
	v_exp_f32_e32 v174, v174
	v_exp_f32_e32 v175, v175
	v_exp_f32_e32 v248, v248
	v_exp_f32_e32 v249, v249
	v_exp_f32_e32 v250, v250
	v_exp_f32_e32 v251, v251
	v_exp_f32_e32 v176, v176
	v_exp_f32_e32 v177, v177
	v_exp_f32_e32 v178, v178
	v_exp_f32_e32 v179, v179
	v_pk_add_f32 v[244:245], v[244:245], 1.0 op_sel_hi:[1,0]
	v_pk_add_f32 v[246:247], v[246:247], 1.0 op_sel_hi:[1,0]
	v_pk_add_f32 v[172:173], v[172:173], 1.0 op_sel_hi:[1,0]
	v_pk_add_f32 v[174:175], v[174:175], 1.0 op_sel_hi:[1,0]
	v_pk_add_f32 v[248:249], v[248:249], 1.0 op_sel_hi:[1,0]
	v_pk_add_f32 v[250:251], v[250:251], 1.0 op_sel_hi:[1,0]
	v_pk_add_f32 v[176:177], v[176:177], 1.0 op_sel_hi:[1,0]
	v_pk_add_f32 v[178:179], v[178:179], 1.0 op_sel_hi:[1,0]
	v_rcp_f32_e32 v244, v244
	v_rcp_f32_e32 v245, v245
	v_rcp_f32_e32 v246, v246
	v_rcp_f32_e32 v247, v247
	v_rcp_f32_e32 v172, v172
	v_rcp_f32_e32 v173, v173
	v_rcp_f32_e32 v174, v174
	v_rcp_f32_e32 v175, v175
	v_pk_mul_f32 v[248:249], v[248:249], v[244:245]
	v_pk_mul_f32 v[250:251], v[250:251], v[246:247]
	v_pk_mul_f32 v[176:177], v[176:177], v[172:173]
	v_pk_mul_f32 v[178:179], v[178:179], v[174:175]
	v_pk_mul_f32 v[88:89], v[88:89], v[248:249]
	v_pk_mul_f32 v[90:91], v[90:91], v[250:251]
	v_pk_mul_f32 v[84:85], v[84:85], v[176:177]
	v_pk_mul_f32 v[86:87], v[86:87], v[178:179]
	global_load_dwordx4 v[172:175], v[218:219], off offset:-1792
	global_load_dwordx4 v[176:179], v[218:219], off offset:2304
	s_waitcnt vmcnt(14)
	v_lshlrev_b32_e32 v244, 16, v180
	v_and_b32_e32 v245, 0xffff0000, v180
	v_lshlrev_b32_e32 v246, 16, v181
	v_and_b32_e32 v247, 0xffff0000, v181
	v_lshlrev_b32_e32 v180, 16, v182
	v_and_b32_e32 v181, 0xffff0000, v182
	v_lshlrev_b32_e32 v182, 16, v183
	v_and_b32_e32 v183, 0xffff0000, v183
	v_lshlrev_b32_e32 v248, 16, v184
	v_and_b32_e32 v249, 0xffff0000, v184
	v_lshlrev_b32_e32 v250, 16, v185
	v_and_b32_e32 v251, 0xffff0000, v185
	v_lshlrev_b32_e32 v184, 16, v186
	v_and_b32_e32 v185, 0xffff0000, v186
	v_lshlrev_b32_e32 v186, 16, v187
	v_and_b32_e32 v187, 0xffff0000, v187
	v_pk_mul_f32 v[244:245], v[244:245], s[34:35] op_sel_hi:[1,0]
	v_pk_mul_f32 v[246:247], v[246:247], s[34:35] op_sel_hi:[1,0]
	v_pk_mul_f32 v[180:181], v[180:181], s[34:35] op_sel_hi:[1,0]
	v_pk_mul_f32 v[182:183], v[182:183], s[34:35] op_sel_hi:[1,0]
	v_pk_mul_f32 v[248:249], v[248:249], s[34:35] op_sel_hi:[1,0]
	v_pk_mul_f32 v[250:251], v[250:251], s[34:35] op_sel_hi:[1,0]
	v_pk_mul_f32 v[184:185], v[184:185], s[34:35] op_sel_hi:[1,0]
	v_pk_mul_f32 v[186:187], v[186:187], s[34:35] op_sel_hi:[1,0]
	v_exp_f32_e32 v244, v244
	v_exp_f32_e32 v245, v245
	v_exp_f32_e32 v246, v246
	v_exp_f32_e32 v247, v247
	v_exp_f32_e32 v180, v180
	v_exp_f32_e32 v181, v181
	v_exp_f32_e32 v182, v182
	v_exp_f32_e32 v183, v183
	v_exp_f32_e32 v248, v248
	v_exp_f32_e32 v249, v249
	v_exp_f32_e32 v250, v250
	v_exp_f32_e32 v251, v251
	v_exp_f32_e32 v184, v184
	v_exp_f32_e32 v185, v185
	v_exp_f32_e32 v186, v186
	v_exp_f32_e32 v187, v187
	v_pk_add_f32 v[244:245], v[244:245], 1.0 op_sel_hi:[1,0]
	v_pk_add_f32 v[246:247], v[246:247], 1.0 op_sel_hi:[1,0]
	v_pk_add_f32 v[180:181], v[180:181], 1.0 op_sel_hi:[1,0]
	v_pk_add_f32 v[182:183], v[182:183], 1.0 op_sel_hi:[1,0]
	v_pk_add_f32 v[248:249], v[248:249], 1.0 op_sel_hi:[1,0]
	v_pk_add_f32 v[250:251], v[250:251], 1.0 op_sel_hi:[1,0]
	v_pk_add_f32 v[184:185], v[184:185], 1.0 op_sel_hi:[1,0]
	v_pk_add_f32 v[186:187], v[186:187], 1.0 op_sel_hi:[1,0]
	v_rcp_f32_e32 v244, v244
	v_rcp_f32_e32 v245, v245
	v_rcp_f32_e32 v246, v246
	v_rcp_f32_e32 v247, v247
	v_rcp_f32_e32 v180, v180
	v_rcp_f32_e32 v181, v181
	v_rcp_f32_e32 v182, v182
	v_rcp_f32_e32 v183, v183
	v_pk_mul_f32 v[248:249], v[248:249], v[244:245]
	v_pk_mul_f32 v[250:251], v[250:251], v[246:247]
	v_pk_mul_f32 v[184:185], v[184:185], v[180:181]
	v_pk_mul_f32 v[186:187], v[186:187], v[182:183]
	v_pk_mul_f32 v[80:81], v[80:81], v[248:249]
	v_pk_mul_f32 v[82:83], v[82:83], v[250:251]
	v_pk_mul_f32 v[76:77], v[76:77], v[184:185]
	v_pk_mul_f32 v[78:79], v[78:79], v[186:187]
	v_add_u32_e32 v213, 176, v1
	v_mad_i64_i32 v[218:219], s[2:3], v213, s20, v[2:3]
	global_load_dwordx4 v[180:183], v[218:219], off offset:-2048
	global_load_dwordx4 v[184:187], v[218:219], off offset:2048
	s_waitcnt vmcnt(14)
	v_lshlrev_b32_e32 v244, 16, v188
	v_and_b32_e32 v245, 0xffff0000, v188
	v_lshlrev_b32_e32 v246, 16, v189
	v_and_b32_e32 v247, 0xffff0000, v189
	v_lshlrev_b32_e32 v188, 16, v190
	v_and_b32_e32 v189, 0xffff0000, v190
	v_lshlrev_b32_e32 v190, 16, v191
	v_and_b32_e32 v191, 0xffff0000, v191
	v_lshlrev_b32_e32 v248, 16, v192
	v_and_b32_e32 v249, 0xffff0000, v192
	v_lshlrev_b32_e32 v250, 16, v193
	v_and_b32_e32 v251, 0xffff0000, v193
	v_lshlrev_b32_e32 v192, 16, v194
	v_and_b32_e32 v193, 0xffff0000, v194
	v_lshlrev_b32_e32 v194, 16, v195
	v_and_b32_e32 v195, 0xffff0000, v195
	v_pk_mul_f32 v[244:245], v[244:245], s[34:35] op_sel_hi:[1,0]
	v_pk_mul_f32 v[246:247], v[246:247], s[34:35] op_sel_hi:[1,0]
	v_pk_mul_f32 v[188:189], v[188:189], s[34:35] op_sel_hi:[1,0]
	v_pk_mul_f32 v[190:191], v[190:191], s[34:35] op_sel_hi:[1,0]
	v_pk_mul_f32 v[248:249], v[248:249], s[34:35] op_sel_hi:[1,0]
	v_pk_mul_f32 v[250:251], v[250:251], s[34:35] op_sel_hi:[1,0]
	v_pk_mul_f32 v[192:193], v[192:193], s[34:35] op_sel_hi:[1,0]
	v_pk_mul_f32 v[194:195], v[194:195], s[34:35] op_sel_hi:[1,0]
	v_exp_f32_e32 v244, v244
	v_exp_f32_e32 v245, v245
	v_exp_f32_e32 v246, v246
	v_exp_f32_e32 v247, v247
	v_exp_f32_e32 v188, v188
	v_exp_f32_e32 v189, v189
	v_exp_f32_e32 v190, v190
	v_exp_f32_e32 v191, v191
	v_exp_f32_e32 v248, v248
	v_exp_f32_e32 v249, v249
	v_exp_f32_e32 v250, v250
	v_exp_f32_e32 v251, v251
	v_exp_f32_e32 v192, v192
	v_exp_f32_e32 v193, v193
	v_exp_f32_e32 v194, v194
	v_exp_f32_e32 v195, v195
	v_pk_add_f32 v[244:245], v[244:245], 1.0 op_sel_hi:[1,0]
	v_pk_add_f32 v[246:247], v[246:247], 1.0 op_sel_hi:[1,0]
	v_pk_add_f32 v[188:189], v[188:189], 1.0 op_sel_hi:[1,0]
	v_pk_add_f32 v[190:191], v[190:191], 1.0 op_sel_hi:[1,0]
	v_pk_add_f32 v[248:249], v[248:249], 1.0 op_sel_hi:[1,0]
	v_pk_add_f32 v[250:251], v[250:251], 1.0 op_sel_hi:[1,0]
	v_pk_add_f32 v[192:193], v[192:193], 1.0 op_sel_hi:[1,0]
	v_pk_add_f32 v[194:195], v[194:195], 1.0 op_sel_hi:[1,0]
	v_rcp_f32_e32 v244, v244
	v_rcp_f32_e32 v245, v245
	v_rcp_f32_e32 v246, v246
	v_rcp_f32_e32 v247, v247
	v_rcp_f32_e32 v188, v188
	v_rcp_f32_e32 v189, v189
	v_rcp_f32_e32 v190, v190
	v_rcp_f32_e32 v191, v191
	v_pk_mul_f32 v[248:249], v[248:249], v[244:245]
	v_pk_mul_f32 v[250:251], v[250:251], v[246:247]
	v_pk_mul_f32 v[192:193], v[192:193], v[188:189]
	v_pk_mul_f32 v[194:195], v[194:195], v[190:191]
	v_pk_mul_f32 v[72:73], v[72:73], v[248:249]
	v_pk_mul_f32 v[74:75], v[74:75], v[250:251]
	v_pk_mul_f32 v[68:69], v[68:69], v[192:193]
	v_pk_mul_f32 v[70:71], v[70:71], v[194:195]
	global_load_dwordx4 v[188:191], v[218:219], off offset:-1792
	global_load_dwordx4 v[192:195], v[218:219], off offset:2304
	s_waitcnt vmcnt(14)
	v_lshlrev_b32_e32 v244, 16, v132
	v_and_b32_e32 v245, 0xffff0000, v132
	v_lshlrev_b32_e32 v246, 16, v133
	v_and_b32_e32 v247, 0xffff0000, v133
	v_lshlrev_b32_e32 v132, 16, v134
	v_and_b32_e32 v133, 0xffff0000, v134
	v_lshlrev_b32_e32 v134, 16, v135
	v_and_b32_e32 v135, 0xffff0000, v135
	v_lshlrev_b32_e32 v248, 16, v136
	v_and_b32_e32 v249, 0xffff0000, v136
	v_lshlrev_b32_e32 v250, 16, v137
	v_and_b32_e32 v251, 0xffff0000, v137
	v_lshlrev_b32_e32 v136, 16, v138
	v_and_b32_e32 v137, 0xffff0000, v138
	v_lshlrev_b32_e32 v138, 16, v139
	v_and_b32_e32 v139, 0xffff0000, v139
	v_pk_mul_f32 v[244:245], v[244:245], s[34:35] op_sel_hi:[1,0]
	v_pk_mul_f32 v[246:247], v[246:247], s[34:35] op_sel_hi:[1,0]
	v_pk_mul_f32 v[132:133], v[132:133], s[34:35] op_sel_hi:[1,0]
	v_pk_mul_f32 v[134:135], v[134:135], s[34:35] op_sel_hi:[1,0]
	v_pk_mul_f32 v[248:249], v[248:249], s[34:35] op_sel_hi:[1,0]
	v_pk_mul_f32 v[250:251], v[250:251], s[34:35] op_sel_hi:[1,0]
	v_pk_mul_f32 v[136:137], v[136:137], s[34:35] op_sel_hi:[1,0]
	v_pk_mul_f32 v[138:139], v[138:139], s[34:35] op_sel_hi:[1,0]
	v_exp_f32_e32 v244, v244
	v_exp_f32_e32 v245, v245
	v_exp_f32_e32 v246, v246
	v_exp_f32_e32 v247, v247
	v_exp_f32_e32 v132, v132
	v_exp_f32_e32 v133, v133
	v_exp_f32_e32 v134, v134
	v_exp_f32_e32 v135, v135
	v_exp_f32_e32 v248, v248
	v_exp_f32_e32 v249, v249
	v_exp_f32_e32 v250, v250
	v_exp_f32_e32 v251, v251
	v_exp_f32_e32 v136, v136
	v_exp_f32_e32 v137, v137
	v_exp_f32_e32 v138, v138
	v_exp_f32_e32 v139, v139
	v_pk_add_f32 v[244:245], v[244:245], 1.0 op_sel_hi:[1,0]
	v_pk_add_f32 v[246:247], v[246:247], 1.0 op_sel_hi:[1,0]
	v_pk_add_f32 v[132:133], v[132:133], 1.0 op_sel_hi:[1,0]
	v_pk_add_f32 v[134:135], v[134:135], 1.0 op_sel_hi:[1,0]
	v_pk_add_f32 v[248:249], v[248:249], 1.0 op_sel_hi:[1,0]
	v_pk_add_f32 v[250:251], v[250:251], 1.0 op_sel_hi:[1,0]
	v_pk_add_f32 v[136:137], v[136:137], 1.0 op_sel_hi:[1,0]
	v_pk_add_f32 v[138:139], v[138:139], 1.0 op_sel_hi:[1,0]
	v_rcp_f32_e32 v244, v244
	v_rcp_f32_e32 v245, v245
	v_rcp_f32_e32 v246, v246
	v_rcp_f32_e32 v247, v247
	v_rcp_f32_e32 v132, v132
	v_rcp_f32_e32 v133, v133
	v_rcp_f32_e32 v134, v134
	v_rcp_f32_e32 v135, v135
	v_pk_mul_f32 v[248:249], v[248:249], v[244:245]
	v_pk_mul_f32 v[250:251], v[250:251], v[246:247]
	v_pk_mul_f32 v[136:137], v[136:137], v[132:133]
	v_pk_mul_f32 v[138:139], v[138:139], v[134:135]
	v_pk_mul_f32 v[64:65], v[64:65], v[248:249]
	v_pk_mul_f32 v[66:67], v[66:67], v[250:251]
	v_pk_mul_f32 v[60:61], v[60:61], v[136:137]
	v_pk_mul_f32 v[62:63], v[62:63], v[138:139]
	s_waitcnt vmcnt(12)
	v_lshlrev_b32_e32 v244, 16, v140
	v_and_b32_e32 v245, 0xffff0000, v140
	v_lshlrev_b32_e32 v246, 16, v141
	v_and_b32_e32 v247, 0xffff0000, v141
	v_lshlrev_b32_e32 v140, 16, v142
	v_and_b32_e32 v141, 0xffff0000, v142
	v_lshlrev_b32_e32 v142, 16, v143
	v_and_b32_e32 v143, 0xffff0000, v143
	v_lshlrev_b32_e32 v248, 16, v144
	v_and_b32_e32 v249, 0xffff0000, v144
	v_lshlrev_b32_e32 v250, 16, v145
	v_and_b32_e32 v251, 0xffff0000, v145
	v_lshlrev_b32_e32 v144, 16, v146
	v_and_b32_e32 v145, 0xffff0000, v146
	v_lshlrev_b32_e32 v146, 16, v147
	v_and_b32_e32 v147, 0xffff0000, v147
	v_pk_mul_f32 v[244:245], v[244:245], s[34:35] op_sel_hi:[1,0]
	v_pk_mul_f32 v[246:247], v[246:247], s[34:35] op_sel_hi:[1,0]
	v_pk_mul_f32 v[140:141], v[140:141], s[34:35] op_sel_hi:[1,0]
	v_pk_mul_f32 v[142:143], v[142:143], s[34:35] op_sel_hi:[1,0]
	v_pk_mul_f32 v[248:249], v[248:249], s[34:35] op_sel_hi:[1,0]
	v_pk_mul_f32 v[250:251], v[250:251], s[34:35] op_sel_hi:[1,0]
	v_pk_mul_f32 v[144:145], v[144:145], s[34:35] op_sel_hi:[1,0]
	v_pk_mul_f32 v[146:147], v[146:147], s[34:35] op_sel_hi:[1,0]
	v_exp_f32_e32 v244, v244
	v_exp_f32_e32 v245, v245
	v_exp_f32_e32 v246, v246
	v_exp_f32_e32 v247, v247
	v_exp_f32_e32 v140, v140
	v_exp_f32_e32 v141, v141
	v_exp_f32_e32 v142, v142
	v_exp_f32_e32 v143, v143
	v_exp_f32_e32 v248, v248
	v_exp_f32_e32 v249, v249
	v_exp_f32_e32 v250, v250
	v_exp_f32_e32 v251, v251
	v_exp_f32_e32 v144, v144
	v_exp_f32_e32 v145, v145
	v_exp_f32_e32 v146, v146
	v_exp_f32_e32 v147, v147
	v_pk_add_f32 v[244:245], v[244:245], 1.0 op_sel_hi:[1,0]
	v_pk_add_f32 v[246:247], v[246:247], 1.0 op_sel_hi:[1,0]
	v_pk_add_f32 v[140:141], v[140:141], 1.0 op_sel_hi:[1,0]
	v_pk_add_f32 v[142:143], v[142:143], 1.0 op_sel_hi:[1,0]
	v_pk_add_f32 v[248:249], v[248:249], 1.0 op_sel_hi:[1,0]
	v_pk_add_f32 v[250:251], v[250:251], 1.0 op_sel_hi:[1,0]
	v_pk_add_f32 v[144:145], v[144:145], 1.0 op_sel_hi:[1,0]
	v_pk_add_f32 v[146:147], v[146:147], 1.0 op_sel_hi:[1,0]
	v_rcp_f32_e32 v244, v244
	v_rcp_f32_e32 v245, v245
	v_rcp_f32_e32 v246, v246
	v_rcp_f32_e32 v247, v247
	v_rcp_f32_e32 v140, v140
	v_rcp_f32_e32 v141, v141
	v_rcp_f32_e32 v142, v142
	v_rcp_f32_e32 v143, v143
	v_pk_mul_f32 v[248:249], v[248:249], v[244:245]
	v_pk_mul_f32 v[250:251], v[250:251], v[246:247]
	v_pk_mul_f32 v[144:145], v[144:145], v[140:141]
	v_pk_mul_f32 v[146:147], v[146:147], v[142:143]
	v_pk_mul_f32 v[56:57], v[56:57], v[248:249]
	v_pk_mul_f32 v[58:59], v[58:59], v[250:251]
	v_pk_mul_f32 v[52:53], v[52:53], v[144:145]
	v_pk_mul_f32 v[54:55], v[54:55], v[146:147]
	s_waitcnt vmcnt(10)
	v_lshlrev_b32_e32 v244, 16, v148
	v_and_b32_e32 v245, 0xffff0000, v148
	v_lshlrev_b32_e32 v246, 16, v149
	v_and_b32_e32 v247, 0xffff0000, v149
	v_lshlrev_b32_e32 v148, 16, v150
	v_and_b32_e32 v149, 0xffff0000, v150
	v_lshlrev_b32_e32 v150, 16, v151
	v_and_b32_e32 v151, 0xffff0000, v151
	v_lshlrev_b32_e32 v248, 16, v152
	v_and_b32_e32 v249, 0xffff0000, v152
	v_lshlrev_b32_e32 v250, 16, v153
	v_and_b32_e32 v251, 0xffff0000, v153
	v_lshlrev_b32_e32 v152, 16, v154
	v_and_b32_e32 v153, 0xffff0000, v154
	v_lshlrev_b32_e32 v154, 16, v155
	v_and_b32_e32 v155, 0xffff0000, v155
	v_pk_mul_f32 v[244:245], v[244:245], s[34:35] op_sel_hi:[1,0]
	v_pk_mul_f32 v[246:247], v[246:247], s[34:35] op_sel_hi:[1,0]
	v_pk_mul_f32 v[148:149], v[148:149], s[34:35] op_sel_hi:[1,0]
	v_pk_mul_f32 v[150:151], v[150:151], s[34:35] op_sel_hi:[1,0]
	v_pk_mul_f32 v[248:249], v[248:249], s[34:35] op_sel_hi:[1,0]
	v_pk_mul_f32 v[250:251], v[250:251], s[34:35] op_sel_hi:[1,0]
	v_pk_mul_f32 v[152:153], v[152:153], s[34:35] op_sel_hi:[1,0]
	v_pk_mul_f32 v[154:155], v[154:155], s[34:35] op_sel_hi:[1,0]
	v_exp_f32_e32 v244, v244
	v_exp_f32_e32 v245, v245
	v_exp_f32_e32 v246, v246
	v_exp_f32_e32 v247, v247
	v_exp_f32_e32 v148, v148
	v_exp_f32_e32 v149, v149
	v_exp_f32_e32 v150, v150
	v_exp_f32_e32 v151, v151
	v_exp_f32_e32 v248, v248
	v_exp_f32_e32 v249, v249
	v_exp_f32_e32 v250, v250
	v_exp_f32_e32 v251, v251
	v_exp_f32_e32 v152, v152
	v_exp_f32_e32 v153, v153
	v_exp_f32_e32 v154, v154
	v_exp_f32_e32 v155, v155
	v_pk_add_f32 v[244:245], v[244:245], 1.0 op_sel_hi:[1,0]
	v_pk_add_f32 v[246:247], v[246:247], 1.0 op_sel_hi:[1,0]
	v_pk_add_f32 v[148:149], v[148:149], 1.0 op_sel_hi:[1,0]
	v_pk_add_f32 v[150:151], v[150:151], 1.0 op_sel_hi:[1,0]
	v_pk_add_f32 v[248:249], v[248:249], 1.0 op_sel_hi:[1,0]
	v_pk_add_f32 v[250:251], v[250:251], 1.0 op_sel_hi:[1,0]
	v_pk_add_f32 v[152:153], v[152:153], 1.0 op_sel_hi:[1,0]
	v_pk_add_f32 v[154:155], v[154:155], 1.0 op_sel_hi:[1,0]
	v_rcp_f32_e32 v244, v244
	v_rcp_f32_e32 v245, v245
	v_rcp_f32_e32 v246, v246
	v_rcp_f32_e32 v247, v247
	v_rcp_f32_e32 v148, v148
	v_rcp_f32_e32 v149, v149
	v_rcp_f32_e32 v150, v150
	v_rcp_f32_e32 v151, v151
	v_pk_mul_f32 v[248:249], v[248:249], v[244:245]
	v_pk_mul_f32 v[250:251], v[250:251], v[246:247]
	v_pk_mul_f32 v[152:153], v[152:153], v[148:149]
	v_pk_mul_f32 v[154:155], v[154:155], v[150:151]
	v_pk_mul_f32 v[48:49], v[48:49], v[248:249]
	v_pk_mul_f32 v[50:51], v[50:51], v[250:251]
	v_pk_mul_f32 v[44:45], v[44:45], v[152:153]
	v_pk_mul_f32 v[46:47], v[46:47], v[154:155]
	s_waitcnt vmcnt(8)
	v_lshlrev_b32_e32 v244, 16, v156
	v_and_b32_e32 v245, 0xffff0000, v156
	v_lshlrev_b32_e32 v246, 16, v157
	v_and_b32_e32 v247, 0xffff0000, v157
	v_lshlrev_b32_e32 v156, 16, v158
	v_and_b32_e32 v157, 0xffff0000, v158
	v_lshlrev_b32_e32 v158, 16, v159
	v_and_b32_e32 v159, 0xffff0000, v159
	v_lshlrev_b32_e32 v248, 16, v160
	v_and_b32_e32 v249, 0xffff0000, v160
	v_lshlrev_b32_e32 v250, 16, v161
	v_and_b32_e32 v251, 0xffff0000, v161
	v_lshlrev_b32_e32 v160, 16, v162
	v_and_b32_e32 v161, 0xffff0000, v162
	v_lshlrev_b32_e32 v162, 16, v163
	v_and_b32_e32 v163, 0xffff0000, v163
	v_pk_mul_f32 v[244:245], v[244:245], s[34:35] op_sel_hi:[1,0]
	v_pk_mul_f32 v[246:247], v[246:247], s[34:35] op_sel_hi:[1,0]
	v_pk_mul_f32 v[156:157], v[156:157], s[34:35] op_sel_hi:[1,0]
	v_pk_mul_f32 v[158:159], v[158:159], s[34:35] op_sel_hi:[1,0]
	v_pk_mul_f32 v[248:249], v[248:249], s[34:35] op_sel_hi:[1,0]
	v_pk_mul_f32 v[250:251], v[250:251], s[34:35] op_sel_hi:[1,0]
	v_pk_mul_f32 v[160:161], v[160:161], s[34:35] op_sel_hi:[1,0]
	v_pk_mul_f32 v[162:163], v[162:163], s[34:35] op_sel_hi:[1,0]
	v_exp_f32_e32 v244, v244
	v_exp_f32_e32 v245, v245
	v_exp_f32_e32 v246, v246
	v_exp_f32_e32 v247, v247
	v_exp_f32_e32 v156, v156
	v_exp_f32_e32 v157, v157
	v_exp_f32_e32 v158, v158
	v_exp_f32_e32 v159, v159
	v_exp_f32_e32 v248, v248
	v_exp_f32_e32 v249, v249
	v_exp_f32_e32 v250, v250
	v_exp_f32_e32 v251, v251
	v_exp_f32_e32 v160, v160
	v_exp_f32_e32 v161, v161
	v_exp_f32_e32 v162, v162
	v_exp_f32_e32 v163, v163
	v_pk_add_f32 v[244:245], v[244:245], 1.0 op_sel_hi:[1,0]
	v_pk_add_f32 v[246:247], v[246:247], 1.0 op_sel_hi:[1,0]
	v_pk_add_f32 v[156:157], v[156:157], 1.0 op_sel_hi:[1,0]
	v_pk_add_f32 v[158:159], v[158:159], 1.0 op_sel_hi:[1,0]
	v_pk_add_f32 v[248:249], v[248:249], 1.0 op_sel_hi:[1,0]
	v_pk_add_f32 v[250:251], v[250:251], 1.0 op_sel_hi:[1,0]
	v_pk_add_f32 v[160:161], v[160:161], 1.0 op_sel_hi:[1,0]
	v_pk_add_f32 v[162:163], v[162:163], 1.0 op_sel_hi:[1,0]
	v_rcp_f32_e32 v244, v244
	v_rcp_f32_e32 v245, v245
	v_rcp_f32_e32 v246, v246
	v_rcp_f32_e32 v247, v247
	v_rcp_f32_e32 v156, v156
	v_rcp_f32_e32 v157, v157
	v_rcp_f32_e32 v158, v158
	v_rcp_f32_e32 v159, v159
	v_pk_mul_f32 v[248:249], v[248:249], v[244:245]
	v_pk_mul_f32 v[250:251], v[250:251], v[246:247]
	v_pk_mul_f32 v[160:161], v[160:161], v[156:157]
	v_pk_mul_f32 v[162:163], v[162:163], v[158:159]
	v_pk_mul_f32 v[40:41], v[40:41], v[248:249]
	v_pk_mul_f32 v[42:43], v[42:43], v[250:251]
	v_pk_mul_f32 v[36:37], v[36:37], v[160:161]
	v_pk_mul_f32 v[38:39], v[38:39], v[162:163]
	s_waitcnt vmcnt(6)
	v_lshlrev_b32_e32 v244, 16, v164
	v_and_b32_e32 v245, 0xffff0000, v164
	v_lshlrev_b32_e32 v246, 16, v165
	v_and_b32_e32 v247, 0xffff0000, v165
	v_lshlrev_b32_e32 v164, 16, v166
	v_and_b32_e32 v165, 0xffff0000, v166
	v_lshlrev_b32_e32 v166, 16, v167
	v_and_b32_e32 v167, 0xffff0000, v167
	v_lshlrev_b32_e32 v248, 16, v168
	v_and_b32_e32 v249, 0xffff0000, v168
	v_lshlrev_b32_e32 v250, 16, v169
	v_and_b32_e32 v251, 0xffff0000, v169
	v_lshlrev_b32_e32 v168, 16, v170
	v_and_b32_e32 v169, 0xffff0000, v170
	v_lshlrev_b32_e32 v170, 16, v171
	v_and_b32_e32 v171, 0xffff0000, v171
	v_pk_mul_f32 v[244:245], v[244:245], s[34:35] op_sel_hi:[1,0]
	v_pk_mul_f32 v[246:247], v[246:247], s[34:35] op_sel_hi:[1,0]
	v_pk_mul_f32 v[164:165], v[164:165], s[34:35] op_sel_hi:[1,0]
	v_pk_mul_f32 v[166:167], v[166:167], s[34:35] op_sel_hi:[1,0]
	v_pk_mul_f32 v[248:249], v[248:249], s[34:35] op_sel_hi:[1,0]
	v_pk_mul_f32 v[250:251], v[250:251], s[34:35] op_sel_hi:[1,0]
	v_pk_mul_f32 v[168:169], v[168:169], s[34:35] op_sel_hi:[1,0]
	v_pk_mul_f32 v[170:171], v[170:171], s[34:35] op_sel_hi:[1,0]
	v_exp_f32_e32 v244, v244
	v_exp_f32_e32 v245, v245
	v_exp_f32_e32 v246, v246
	v_exp_f32_e32 v247, v247
	v_exp_f32_e32 v164, v164
	v_exp_f32_e32 v165, v165
	v_exp_f32_e32 v166, v166
	v_exp_f32_e32 v167, v167
	v_exp_f32_e32 v248, v248
	v_exp_f32_e32 v249, v249
	v_exp_f32_e32 v250, v250
	v_exp_f32_e32 v251, v251
	v_exp_f32_e32 v168, v168
	v_exp_f32_e32 v169, v169
	v_exp_f32_e32 v170, v170
	v_exp_f32_e32 v171, v171
	v_pk_add_f32 v[244:245], v[244:245], 1.0 op_sel_hi:[1,0]
	v_pk_add_f32 v[246:247], v[246:247], 1.0 op_sel_hi:[1,0]
	v_pk_add_f32 v[164:165], v[164:165], 1.0 op_sel_hi:[1,0]
	v_pk_add_f32 v[166:167], v[166:167], 1.0 op_sel_hi:[1,0]
	v_pk_add_f32 v[248:249], v[248:249], 1.0 op_sel_hi:[1,0]
	v_pk_add_f32 v[250:251], v[250:251], 1.0 op_sel_hi:[1,0]
	v_pk_add_f32 v[168:169], v[168:169], 1.0 op_sel_hi:[1,0]
	v_pk_add_f32 v[170:171], v[170:171], 1.0 op_sel_hi:[1,0]
	v_rcp_f32_e32 v244, v244
	v_rcp_f32_e32 v245, v245
	v_rcp_f32_e32 v246, v246
	v_rcp_f32_e32 v247, v247
	v_rcp_f32_e32 v164, v164
	v_rcp_f32_e32 v165, v165
	v_rcp_f32_e32 v166, v166
	v_rcp_f32_e32 v167, v167
	v_pk_mul_f32 v[248:249], v[248:249], v[244:245]
	v_pk_mul_f32 v[250:251], v[250:251], v[246:247]
	v_pk_mul_f32 v[168:169], v[168:169], v[164:165]
	v_pk_mul_f32 v[170:171], v[170:171], v[166:167]
	v_pk_mul_f32 v[32:33], v[32:33], v[248:249]
	v_pk_mul_f32 v[34:35], v[34:35], v[250:251]
	v_pk_mul_f32 v[28:29], v[28:29], v[168:169]
	v_pk_mul_f32 v[30:31], v[30:31], v[170:171]
	s_waitcnt vmcnt(4)
	v_lshlrev_b32_e32 v244, 16, v172
	v_and_b32_e32 v245, 0xffff0000, v172
	v_lshlrev_b32_e32 v246, 16, v173
	v_and_b32_e32 v247, 0xffff0000, v173
	v_lshlrev_b32_e32 v172, 16, v174
	v_and_b32_e32 v173, 0xffff0000, v174
	v_lshlrev_b32_e32 v174, 16, v175
	v_and_b32_e32 v175, 0xffff0000, v175
	v_lshlrev_b32_e32 v248, 16, v176
	v_and_b32_e32 v249, 0xffff0000, v176
	v_lshlrev_b32_e32 v250, 16, v177
	v_and_b32_e32 v251, 0xffff0000, v177
	v_lshlrev_b32_e32 v176, 16, v178
	v_and_b32_e32 v177, 0xffff0000, v178
	v_lshlrev_b32_e32 v178, 16, v179
	v_and_b32_e32 v179, 0xffff0000, v179
	v_pk_mul_f32 v[244:245], v[244:245], s[34:35] op_sel_hi:[1,0]
	v_pk_mul_f32 v[246:247], v[246:247], s[34:35] op_sel_hi:[1,0]
	v_pk_mul_f32 v[172:173], v[172:173], s[34:35] op_sel_hi:[1,0]
	v_pk_mul_f32 v[174:175], v[174:175], s[34:35] op_sel_hi:[1,0]
	v_pk_mul_f32 v[248:249], v[248:249], s[34:35] op_sel_hi:[1,0]
	v_pk_mul_f32 v[250:251], v[250:251], s[34:35] op_sel_hi:[1,0]
	v_pk_mul_f32 v[176:177], v[176:177], s[34:35] op_sel_hi:[1,0]
	v_pk_mul_f32 v[178:179], v[178:179], s[34:35] op_sel_hi:[1,0]
	v_exp_f32_e32 v244, v244
	v_exp_f32_e32 v245, v245
	v_exp_f32_e32 v246, v246
	v_exp_f32_e32 v247, v247
	v_exp_f32_e32 v172, v172
	v_exp_f32_e32 v173, v173
	v_exp_f32_e32 v174, v174
	v_exp_f32_e32 v175, v175
	v_exp_f32_e32 v248, v248
	v_exp_f32_e32 v249, v249
	v_exp_f32_e32 v250, v250
	v_exp_f32_e32 v251, v251
	v_exp_f32_e32 v176, v176
	v_exp_f32_e32 v177, v177
	v_exp_f32_e32 v178, v178
	v_exp_f32_e32 v179, v179
	v_pk_add_f32 v[244:245], v[244:245], 1.0 op_sel_hi:[1,0]
	v_pk_add_f32 v[246:247], v[246:247], 1.0 op_sel_hi:[1,0]
	v_pk_add_f32 v[172:173], v[172:173], 1.0 op_sel_hi:[1,0]
	v_pk_add_f32 v[174:175], v[174:175], 1.0 op_sel_hi:[1,0]
	v_pk_add_f32 v[248:249], v[248:249], 1.0 op_sel_hi:[1,0]
	v_pk_add_f32 v[250:251], v[250:251], 1.0 op_sel_hi:[1,0]
	v_pk_add_f32 v[176:177], v[176:177], 1.0 op_sel_hi:[1,0]
	v_pk_add_f32 v[178:179], v[178:179], 1.0 op_sel_hi:[1,0]
	v_rcp_f32_e32 v244, v244
	v_rcp_f32_e32 v245, v245
	v_rcp_f32_e32 v246, v246
	v_rcp_f32_e32 v247, v247
	v_rcp_f32_e32 v172, v172
	v_rcp_f32_e32 v173, v173
	v_rcp_f32_e32 v174, v174
	v_rcp_f32_e32 v175, v175
	v_pk_mul_f32 v[248:249], v[248:249], v[244:245]
	v_pk_mul_f32 v[250:251], v[250:251], v[246:247]
	v_pk_mul_f32 v[176:177], v[176:177], v[172:173]
	v_pk_mul_f32 v[178:179], v[178:179], v[174:175]
	v_pk_mul_f32 v[24:25], v[24:25], v[248:249]
	v_pk_mul_f32 v[26:27], v[26:27], v[250:251]
	v_pk_mul_f32 v[20:21], v[20:21], v[176:177]
	v_pk_mul_f32 v[22:23], v[22:23], v[178:179]
	s_waitcnt vmcnt(2)
	v_lshlrev_b32_e32 v244, 16, v180
	v_and_b32_e32 v245, 0xffff0000, v180
	v_lshlrev_b32_e32 v246, 16, v181
	v_and_b32_e32 v247, 0xffff0000, v181
	v_lshlrev_b32_e32 v180, 16, v182
	v_and_b32_e32 v181, 0xffff0000, v182
	v_lshlrev_b32_e32 v182, 16, v183
	v_and_b32_e32 v183, 0xffff0000, v183
	v_lshlrev_b32_e32 v248, 16, v184
	v_and_b32_e32 v249, 0xffff0000, v184
	v_lshlrev_b32_e32 v250, 16, v185
	v_and_b32_e32 v251, 0xffff0000, v185
	v_lshlrev_b32_e32 v184, 16, v186
	v_and_b32_e32 v185, 0xffff0000, v186
	v_lshlrev_b32_e32 v186, 16, v187
	v_and_b32_e32 v187, 0xffff0000, v187
	v_pk_mul_f32 v[244:245], v[244:245], s[34:35] op_sel_hi:[1,0]
	v_pk_mul_f32 v[246:247], v[246:247], s[34:35] op_sel_hi:[1,0]
	v_pk_mul_f32 v[180:181], v[180:181], s[34:35] op_sel_hi:[1,0]
	v_pk_mul_f32 v[182:183], v[182:183], s[34:35] op_sel_hi:[1,0]
	v_pk_mul_f32 v[248:249], v[248:249], s[34:35] op_sel_hi:[1,0]
	v_pk_mul_f32 v[250:251], v[250:251], s[34:35] op_sel_hi:[1,0]
	v_pk_mul_f32 v[184:185], v[184:185], s[34:35] op_sel_hi:[1,0]
	v_pk_mul_f32 v[186:187], v[186:187], s[34:35] op_sel_hi:[1,0]
	v_exp_f32_e32 v244, v244
	v_exp_f32_e32 v245, v245
	v_exp_f32_e32 v246, v246
	v_exp_f32_e32 v247, v247
	v_exp_f32_e32 v180, v180
	v_exp_f32_e32 v181, v181
	v_exp_f32_e32 v182, v182
	v_exp_f32_e32 v183, v183
	v_exp_f32_e32 v248, v248
	v_exp_f32_e32 v249, v249
	v_exp_f32_e32 v250, v250
	v_exp_f32_e32 v251, v251
	v_exp_f32_e32 v184, v184
	v_exp_f32_e32 v185, v185
	v_exp_f32_e32 v186, v186
	v_exp_f32_e32 v187, v187
	v_pk_add_f32 v[244:245], v[244:245], 1.0 op_sel_hi:[1,0]
	v_pk_add_f32 v[246:247], v[246:247], 1.0 op_sel_hi:[1,0]
	v_pk_add_f32 v[180:181], v[180:181], 1.0 op_sel_hi:[1,0]
	v_pk_add_f32 v[182:183], v[182:183], 1.0 op_sel_hi:[1,0]
	v_pk_add_f32 v[248:249], v[248:249], 1.0 op_sel_hi:[1,0]
	v_pk_add_f32 v[250:251], v[250:251], 1.0 op_sel_hi:[1,0]
	v_pk_add_f32 v[184:185], v[184:185], 1.0 op_sel_hi:[1,0]
	v_pk_add_f32 v[186:187], v[186:187], 1.0 op_sel_hi:[1,0]
	v_rcp_f32_e32 v244, v244
	v_rcp_f32_e32 v245, v245
	v_rcp_f32_e32 v246, v246
	v_rcp_f32_e32 v247, v247
	v_rcp_f32_e32 v180, v180
	v_rcp_f32_e32 v181, v181
	v_rcp_f32_e32 v182, v182
	v_rcp_f32_e32 v183, v183
	v_pk_mul_f32 v[248:249], v[248:249], v[244:245]
	v_pk_mul_f32 v[250:251], v[250:251], v[246:247]
	v_pk_mul_f32 v[184:185], v[184:185], v[180:181]
	v_pk_mul_f32 v[186:187], v[186:187], v[182:183]
	v_pk_mul_f32 v[16:17], v[16:17], v[248:249]
	v_pk_mul_f32 v[18:19], v[18:19], v[250:251]
	v_pk_mul_f32 v[12:13], v[12:13], v[184:185]
	v_pk_mul_f32 v[14:15], v[14:15], v[186:187]
	s_waitcnt vmcnt(0)
	v_lshlrev_b32_e32 v244, 16, v188
	v_and_b32_e32 v245, 0xffff0000, v188
	v_lshlrev_b32_e32 v246, 16, v189
	v_and_b32_e32 v247, 0xffff0000, v189
	v_lshlrev_b32_e32 v188, 16, v190
	v_and_b32_e32 v189, 0xffff0000, v190
	v_lshlrev_b32_e32 v190, 16, v191
	v_and_b32_e32 v191, 0xffff0000, v191
	v_lshlrev_b32_e32 v248, 16, v192
	v_and_b32_e32 v249, 0xffff0000, v192
	v_lshlrev_b32_e32 v250, 16, v193
	v_and_b32_e32 v251, 0xffff0000, v193
	v_lshlrev_b32_e32 v192, 16, v194
	v_and_b32_e32 v193, 0xffff0000, v194
	v_lshlrev_b32_e32 v194, 16, v195
	v_and_b32_e32 v195, 0xffff0000, v195
	v_pk_mul_f32 v[244:245], v[244:245], s[34:35] op_sel_hi:[1,0]
	v_pk_mul_f32 v[246:247], v[246:247], s[34:35] op_sel_hi:[1,0]
	v_pk_mul_f32 v[188:189], v[188:189], s[34:35] op_sel_hi:[1,0]
	v_pk_mul_f32 v[190:191], v[190:191], s[34:35] op_sel_hi:[1,0]
	v_pk_mul_f32 v[248:249], v[248:249], s[34:35] op_sel_hi:[1,0]
	v_pk_mul_f32 v[250:251], v[250:251], s[34:35] op_sel_hi:[1,0]
	v_pk_mul_f32 v[192:193], v[192:193], s[34:35] op_sel_hi:[1,0]
	v_pk_mul_f32 v[194:195], v[194:195], s[34:35] op_sel_hi:[1,0]
	v_exp_f32_e32 v244, v244
	v_exp_f32_e32 v245, v245
	v_exp_f32_e32 v246, v246
	v_exp_f32_e32 v247, v247
	v_exp_f32_e32 v188, v188
	v_exp_f32_e32 v189, v189
	v_exp_f32_e32 v190, v190
	v_exp_f32_e32 v191, v191
	v_exp_f32_e32 v248, v248
	v_exp_f32_e32 v249, v249
	v_exp_f32_e32 v250, v250
	v_exp_f32_e32 v251, v251
	v_exp_f32_e32 v192, v192
	v_exp_f32_e32 v193, v193
	v_exp_f32_e32 v194, v194
	v_exp_f32_e32 v195, v195
	v_pk_add_f32 v[244:245], v[244:245], 1.0 op_sel_hi:[1,0]
	v_pk_add_f32 v[246:247], v[246:247], 1.0 op_sel_hi:[1,0]
	v_pk_add_f32 v[188:189], v[188:189], 1.0 op_sel_hi:[1,0]
	v_pk_add_f32 v[190:191], v[190:191], 1.0 op_sel_hi:[1,0]
	v_pk_add_f32 v[248:249], v[248:249], 1.0 op_sel_hi:[1,0]
	v_pk_add_f32 v[250:251], v[250:251], 1.0 op_sel_hi:[1,0]
	v_pk_add_f32 v[192:193], v[192:193], 1.0 op_sel_hi:[1,0]
	v_pk_add_f32 v[194:195], v[194:195], 1.0 op_sel_hi:[1,0]
	v_rcp_f32_e32 v244, v244
	v_rcp_f32_e32 v245, v245
	v_rcp_f32_e32 v246, v246
	v_rcp_f32_e32 v247, v247
	v_rcp_f32_e32 v188, v188
	v_rcp_f32_e32 v189, v189
	v_rcp_f32_e32 v190, v190
	v_rcp_f32_e32 v191, v191
	v_pk_mul_f32 v[248:249], v[248:249], v[244:245]
	v_pk_mul_f32 v[250:251], v[250:251], v[246:247]
	v_pk_mul_f32 v[192:193], v[192:193], v[188:189]
	v_pk_mul_f32 v[194:195], v[194:195], v[190:191]
	v_pk_mul_f32 v[8:9], v[8:9], v[248:249]
	v_pk_mul_f32 v[10:11], v[10:11], v[250:251]
	v_pk_mul_f32 v[4:5], v[4:5], v[192:193]
	v_pk_mul_f32 v[6:7], v[6:7], v[194:195]
